# v23 with the LDS write block after the 7th and the V fragment reads after the 10th QK MFMA
# speedup vs baseline: 1.0044x; 1.0044x over previous
.LBB0_1039:
	s_waitcnt lgkmcnt(11)
	v_mfma_f32_32x32x16_bf16 v[64:79], v[172:175], v[100:103], 0
	v_exp_f32_e32 v32, v32
	v_exp_f32_e32 v33, v33
	v_exp_f32_e32 v34, v34
	s_waitcnt lgkmcnt(9)
	v_mfma_f32_32x32x16_bf16 v[80:95], v[180:183], v[100:103], 0
	v_add_f32_e32 v251, v32, v33
	v_cvt_pk_bf16_f32 v48, v48, v49
	v_exp_f32_e32 v35, v35
	v_add_f32_e32 v251, v34, v251
	v_mfma_f32_32x32x16_bf16 v[64:79], v[152:155], v[104:107], v[64:79]
	v_exp_f32_e32 v36, v36
	v_add_f32_e32 v251, v35, v251
	v_cvt_pk_bf16_f32 v49, v50, v51
	v_exp_f32_e32 v37, v37
	s_waitcnt lgkmcnt(8)
	v_mfma_f32_32x32x16_bf16 v[80:95], v[164:167], v[104:107], v[80:95]
	v_add_f32_e32 v251, v36, v251
	v_exp_f32_e32 v38, v38
	v_add_f32_e32 v251, v37, v251
	v_cvt_pk_bf16_f32 v50, v52, v53
	s_waitcnt lgkmcnt(7)
	v_mfma_f32_32x32x16_bf16 v[64:79], v[156:159], v[108:111], v[64:79]
	v_exp_f32_e32 v39, v39
	v_add_f32_e32 v251, v38, v251
	v_exp_f32_e32 v40, v40
	s_waitcnt lgkmcnt(5)
	v_mfma_f32_32x32x16_bf16 v[80:95], v[176:179], v[108:111], v[80:95]
	v_add_f32_e32 v251, v39, v251
	v_cvt_pk_bf16_f32 v51, v54, v55
	v_exp_f32_e32 v41, v41
	v_add_f32_e32 v251, v40, v251
	v_mfma_f32_32x32x16_bf16 v[64:79], v[140:143], v[112:115], v[64:79]
	v_exp_f32_e32 v42, v42
	v_add_f32_e32 v251, v41, v251
	v_cvt_pk_bf16_f32 v52, v56, v57
	v_exp_f32_e32 v43, v43
	s_mul_i32 s6, s91, 0x3400
	s_add_i32 s7, s6, 0

	v_add_u32_e32 v253, s7, v96
	s_waitcnt vmcnt(1)
	ds_write_b128 v253, v[128:131]
	s_and_saveexec_b64 s[4:5], s[2:3]
	v_add_u32_e32 v253, s7, v185
	ds_write_b128 v253, v[124:127]
	s_or_b64 exec, exec, s[4:5]
	v_lshl_add_u64 v[200:201], s[100:101], 0, v[190:191]

	v_add_u32_e32 v206, 0xc000, v208
	v_lshl_add_u64 v[128:129], s[98:99], 0, v[188:189]
	s_nop 0
	global_load_dwordx4 v[128:131], v[128:129], off
	s_waitcnt vmcnt(1)
	ds_write2_b64 v206, v[132:133], v[134:135] offset1:2

	s_and_saveexec_b64 s[4:5], s[2:3]
	s_cbranch_execz .LatA_h0
	v_lshl_add_u64 v[124:125], s[98:99], 0, v[186:187]
	s_nop 0
	global_load_dwordx4 v[124:127], v[124:125], off
.LatA_h0:
	s_or_b64 exec, exec, s[4:5]
	global_load_dwordx4 v[132:135], v[200:201], off offset:256

	s_waitcnt lgkmcnt(6)
	v_mfma_f32_32x32x16_bf16 v[80:95], v[160:163], v[112:115], v[80:95]
	v_add_f32_e32 v251, v42, v251
	v_exp_f32_e32 v44, v44
	v_add_f32_e32 v251, v43, v251
	v_cvt_pk_bf16_f32 v53, v58, v59
	s_waitcnt lgkmcnt(5)
	v_mfma_f32_32x32x16_bf16 v[64:79], v[148:151], v[116:119], v[64:79]
	v_exp_f32_e32 v45, v45
	v_add_f32_e32 v251, v44, v251
	v_exp_f32_e32 v46, v46
	v_add_f32_e32 v251, v45, v251
	s_waitcnt lgkmcnt(3)
	v_mfma_f32_32x32x16_bf16 v[80:95], v[168:171], v[116:119], v[80:95]
	v_cvt_pk_bf16_f32 v54, v60, v61
	v_exp_f32_e32 v47, v47
	v_add_f32_e32 v251, v46, v251
	v_add_f32_e32 v251, v47, v251
	v_add_u32_e32 v198, v207, v184
	ds_read_b128 v[210:213], v198 offset:44544
	ds_read_b128 v[214:217], v198 offset:39936
	ds_read_b128 v[218:221], v198 offset:39968
	ds_read_b128 v[222:225], v198 offset:44576
	ds_read_b128 v[226:229], v198 offset:40000
	ds_read_b128 v[230:233], v198 offset:44608
	ds_read_b128 v[234:237], v198 offset:40032
	ds_read_b128 v[238:241], v198 offset:44640
	v_mfma_f32_32x32x16_bf16 v[64:79], v[136:139], v[120:123], v[64:79]
	v_cvt_pk_bf16_f32 v55, v62, v63
	v_cvt_pk_bf16_f32 v32, v32, v33
	v_cvt_pk_bf16_f32 v33, v34, v35
	v_cvt_pk_bf16_f32 v34, v36, v37
	v_cvt_pk_bf16_f32 v35, v38, v39
	v_cvt_pk_bf16_f32 v36, v40, v41
	s_waitcnt lgkmcnt(10)
	v_mfma_f32_32x32x16_bf16 v[80:95], v[144:147], v[120:123], v[80:95]
	v_cvt_pk_bf16_f32 v37, v42, v43
	v_cvt_pk_bf16_f32 v38, v44, v45
	v_cvt_pk_bf16_f32 v39, v46, v47
	v_add_f32_e32 v195, v195, v251
	v_add_f32_e32 v199, v199, v195
	s_waitcnt lgkmcnt(0)
	s_barrier

	v_add_u32_e32 v197, s6, v204
	s_setprio 1
	v_mfma_f32_32x32x16_bf16 v[0:15], v[48:51], v[210:213], v[0:15]
	ds_read_b128 v[172:175], v197
	ds_read_b128 v[152:155], v197 offset:32
	v_mfma_f32_32x32x16_bf16 v[0:15], v[52:55], v[222:225], v[0:15]
	ds_read_b128 v[180:183], v197 offset:6656
	ds_read_b128 v[164:167], v197 offset:6688
	v_mfma_f32_32x32x16_bf16 v[0:15], v[32:35], v[230:233], v[0:15]
	ds_read_b128 v[156:159], v197 offset:64
	ds_read_b128 v[140:143], v197 offset:96
	v_exp_f32_e32 v64, v64
	v_exp_f32_e32 v65, v65
	v_exp_f32_e32 v66, v66
	v_add_f32_e32 v195, v64, v65
	v_mfma_f32_32x32x16_bf16 v[0:15], v[36:39], v[238:241], v[0:15]
	s_setprio 0
	ds_read_b128 v[176:179], v197 offset:6720
	ds_read_b128 v[160:163], v197 offset:6752
	v_exp_f32_e32 v67, v67
	v_add_f32_e32 v195, v66, v195
	v_exp_f32_e32 v68, v68
	v_add_f32_e32 v195, v67, v195
	v_exp_f32_e32 v69, v69
	v_add_f32_e32 v195, v68, v195
	v_mfma_f32_32x32x16_bf16 v[16:31], v[48:51], v[214:217], v[16:31]
	ds_read_b128 v[148:151], v197 offset:128
	ds_read_b128 v[136:139], v197 offset:160
	v_exp_f32_e32 v70, v70
	v_add_f32_e32 v195, v69, v195
	v_exp_f32_e32 v71, v71
	v_add_f32_e32 v195, v70, v195
	v_exp_f32_e32 v72, v72
	v_mfma_f32_32x32x16_bf16 v[16:31], v[52:55], v[218:221], v[16:31]
	ds_read_b128 v[168:171], v197 offset:6784
	ds_read_b128 v[144:147], v197 offset:6816
	v_add_f32_e32 v195, v71, v195
	v_exp_f32_e32 v73, v73
	v_add_f32_e32 v195, v72, v195
	v_exp_f32_e32 v74, v74
	v_add_f32_e32 v195, v73, v195
	v_mfma_f32_32x32x16_bf16 v[16:31], v[32:35], v[226:229], v[16:31]
	v_exp_f32_e32 v75, v75
	v_add_f32_e32 v195, v74, v195
	v_exp_f32_e32 v76, v76
	v_add_f32_e32 v195, v75, v195
	v_exp_f32_e32 v77, v77
	v_mfma_f32_32x32x16_bf16 v[16:31], v[36:39], v[234:237], v[16:31]
	v_add_f32_e32 v195, v76, v195
	v_exp_f32_e32 v78, v78
	v_add_f32_e32 v195, v77, v195
	v_exp_f32_e32 v79, v79
	v_add_f32_e32 v195, v78, v195
	v_add_f32_e32 v195, v79, v195
	s_waitcnt lgkmcnt(11)
	v_mfma_f32_32x32x16_bf16 v[48:63], v[172:175], v[100:103], 0
	v_exp_f32_e32 v80, v80
	v_exp_f32_e32 v81, v81
	v_exp_f32_e32 v82, v82
	s_waitcnt lgkmcnt(9)
	v_mfma_f32_32x32x16_bf16 v[32:47], v[180:183], v[100:103], 0
	v_add_f32_e32 v251, v80, v81
	v_cvt_pk_bf16_f32 v64, v64, v65
	v_exp_f32_e32 v83, v83
	v_add_f32_e32 v251, v82, v251
	v_mfma_f32_32x32x16_bf16 v[48:63], v[152:155], v[104:107], v[48:63]
	v_exp_f32_e32 v84, v84
	v_add_f32_e32 v251, v83, v251
	v_cvt_pk_bf16_f32 v65, v66, v67
	v_exp_f32_e32 v85, v85
	s_waitcnt lgkmcnt(8)
	v_mfma_f32_32x32x16_bf16 v[32:47], v[164:167], v[104:107], v[32:47]
	v_add_f32_e32 v251, v84, v251
	v_exp_f32_e32 v86, v86
	v_add_f32_e32 v251, v85, v251
	v_cvt_pk_bf16_f32 v66, v68, v69
	s_waitcnt lgkmcnt(7)
	v_mfma_f32_32x32x16_bf16 v[48:63], v[156:159], v[108:111], v[48:63]
	v_exp_f32_e32 v87, v87
	v_add_f32_e32 v251, v86, v251
	v_exp_f32_e32 v88, v88
	s_waitcnt lgkmcnt(5)
	v_mfma_f32_32x32x16_bf16 v[32:47], v[176:179], v[108:111], v[32:47]
	v_add_f32_e32 v251, v87, v251
	v_cvt_pk_bf16_f32 v67, v70, v71
	v_exp_f32_e32 v89, v89
	v_add_f32_e32 v251, v88, v251
	v_mfma_f32_32x32x16_bf16 v[48:63], v[140:143], v[112:115], v[48:63]
	v_exp_f32_e32 v90, v90
	v_add_f32_e32 v251, v89, v251
	v_cvt_pk_bf16_f32 v68, v72, v73
	v_exp_f32_e32 v91, v91
	s_add_i32 s4, s91, 1
	s_cmp_lg_u32 s91, 2
	s_cselect_b32 s74, s4, 0
	s_mul_i32 s6, s74, 0x3400
	s_add_i32 s7, s6, 0
	s_add_u32 s98, s98, 0x3000
	s_addc_u32 s99, s99, 0

	v_add_u32_e32 v253, s7, v96
	s_waitcnt vmcnt(1)
	ds_write_b128 v253, v[128:131]
	s_and_saveexec_b64 s[4:5], s[2:3]
	v_add_u32_e32 v253, s7, v185
	ds_write_b128 v253, v[124:127]
	s_or_b64 exec, exec, s[4:5]
	v_lshl_add_u64 v[200:201], s[100:101], 0, v[190:191]

	s_waitcnt vmcnt(0)
	ds_write2_b64 v205, v[132:133], v[134:135] offset0:128 offset1:130
	v_lshl_add_u64 v[128:129], s[98:99], 0, v[188:189]
	s_nop 0
	global_load_dwordx4 v[128:131], v[128:129], off

	s_and_saveexec_b64 s[4:5], s[2:3]
	s_cbranch_execz .LatA_h1
	v_lshl_add_u64 v[124:125], s[98:99], 0, v[186:187]
	s_nop 0
	global_load_dwordx4 v[124:127], v[124:125], off
.LatA_h1:
	s_or_b64 exec, exec, s[4:5]
	global_load_dwordx4 v[132:135], v[200:201], off offset:384

	s_sub_u32 s98, s98, 0x3000
	s_subb_u32 s99, s99, 0

	s_waitcnt lgkmcnt(6)
	v_mfma_f32_32x32x16_bf16 v[32:47], v[160:163], v[112:115], v[32:47]
	v_add_f32_e32 v251, v90, v251
	v_exp_f32_e32 v92, v92
	v_add_f32_e32 v251, v91, v251
	v_cvt_pk_bf16_f32 v69, v74, v75
	s_waitcnt lgkmcnt(5)
	v_mfma_f32_32x32x16_bf16 v[48:63], v[148:151], v[116:119], v[48:63]
	v_exp_f32_e32 v93, v93
	v_add_f32_e32 v251, v92, v251
	v_exp_f32_e32 v94, v94
	v_add_f32_e32 v251, v93, v251
	s_waitcnt lgkmcnt(3)
	v_mfma_f32_32x32x16_bf16 v[32:47], v[168:171], v[116:119], v[32:47]
	v_cvt_pk_bf16_f32 v70, v76, v77
	v_exp_f32_e32 v95, v95
	v_add_f32_e32 v251, v94, v251
	v_add_f32_e32 v251, v95, v251
	v_add_u32_e32 v198, v207, v184
	ds_read_b128 v[210:213], v198 offset:53760
	ds_read_b128 v[214:217], v198 offset:49152
	ds_read_b128 v[218:221], v198 offset:49184
	ds_read_b128 v[222:225], v198 offset:53792
	ds_read_b128 v[226:229], v198 offset:49216
	ds_read_b128 v[230:233], v198 offset:53824
	ds_read_b128 v[234:237], v198 offset:49248
	ds_read_b128 v[238:241], v198 offset:53856
	v_mfma_f32_32x32x16_bf16 v[48:63], v[136:139], v[120:123], v[48:63]
	v_cvt_pk_bf16_f32 v71, v78, v79
	v_cvt_pk_bf16_f32 v80, v80, v81
	v_cvt_pk_bf16_f32 v81, v82, v83
	v_cvt_pk_bf16_f32 v82, v84, v85
	v_cvt_pk_bf16_f32 v83, v86, v87
	v_cvt_pk_bf16_f32 v84, v88, v89
	s_waitcnt lgkmcnt(10)
	v_mfma_f32_32x32x16_bf16 v[32:47], v[144:147], v[120:123], v[32:47]
	v_cvt_pk_bf16_f32 v85, v90, v91
	v_cvt_pk_bf16_f32 v86, v92, v93
	v_cvt_pk_bf16_f32 v87, v94, v95
	v_add_f32_e32 v195, v195, v251
	v_add_f32_e32 v199, v199, v195
	s_add_i32 s92, s79, 2
	s_waitcnt lgkmcnt(0)
	s_barrier

	s_cmp_ge_u32 s92, s87
	s_cbranch_scc1 .LatA_yplain

	v_add_u32_e32 v197, s6, v204
	s_setprio 1
	v_mfma_f32_32x32x16_bf16 v[0:15], v[64:67], v[210:213], v[0:15]
	ds_read_b128 v[172:175], v197
	ds_read_b128 v[152:155], v197 offset:32
	v_mfma_f32_32x32x16_bf16 v[0:15], v[68:71], v[222:225], v[0:15]
	ds_read_b128 v[180:183], v197 offset:6656
	ds_read_b128 v[164:167], v197 offset:6688
	v_mfma_f32_32x32x16_bf16 v[0:15], v[80:83], v[230:233], v[0:15]
	ds_read_b128 v[156:159], v197 offset:64
	ds_read_b128 v[140:143], v197 offset:96
	v_exp_f32_e32 v48, v48
	v_exp_f32_e32 v49, v49
	v_exp_f32_e32 v50, v50
	v_add_f32_e32 v195, v48, v49
	v_mfma_f32_32x32x16_bf16 v[0:15], v[84:87], v[238:241], v[0:15]
	s_setprio 0
	ds_read_b128 v[176:179], v197 offset:6720
	ds_read_b128 v[160:163], v197 offset:6752
	v_exp_f32_e32 v51, v51
	v_add_f32_e32 v195, v50, v195
	v_exp_f32_e32 v52, v52
	v_add_f32_e32 v195, v51, v195
	v_exp_f32_e32 v53, v53
	v_add_f32_e32 v195, v52, v195
	v_mfma_f32_32x32x16_bf16 v[16:31], v[64:67], v[214:217], v[16:31]
	ds_read_b128 v[148:151], v197 offset:128
	ds_read_b128 v[136:139], v197 offset:160
	v_exp_f32_e32 v54, v54
	v_add_f32_e32 v195, v53, v195
	v_exp_f32_e32 v55, v55
	v_add_f32_e32 v195, v54, v195
	v_exp_f32_e32 v56, v56
	v_mfma_f32_32x32x16_bf16 v[16:31], v[68:71], v[218:221], v[16:31]
	ds_read_b128 v[168:171], v197 offset:6784
	ds_read_b128 v[144:147], v197 offset:6816
	v_add_f32_e32 v195, v55, v195
	v_exp_f32_e32 v57, v57
	v_add_f32_e32 v195, v56, v195
	v_exp_f32_e32 v58, v58
	v_add_f32_e32 v195, v57, v195
	v_mfma_f32_32x32x16_bf16 v[16:31], v[80:83], v[226:229], v[16:31]
	v_exp_f32_e32 v59, v59
	v_add_f32_e32 v195, v58, v195
	v_exp_f32_e32 v60, v60
	v_add_f32_e32 v195, v59, v195
	v_exp_f32_e32 v61, v61
	v_mfma_f32_32x32x16_bf16 v[16:31], v[84:87], v[234:237], v[16:31]
	v_add_f32_e32 v195, v60, v195
	v_exp_f32_e32 v62, v62
	v_add_f32_e32 v195, v61, v195
	v_exp_f32_e32 v63, v63
	v_add_f32_e32 v195, v62, v195
	v_add_f32_e32 v195, v63, v195
	s_branch .LatA_ctl

.LBB0_1106:
	s_waitcnt lgkmcnt(11)
	v_mfma_f32_32x32x16_bf16 v[64:79], v[172:175], v[100:103], 0
	v_exp_f32_e32 v32, v32
	v_exp_f32_e32 v33, v33
	v_exp_f32_e32 v34, v34
	s_waitcnt lgkmcnt(9)
	v_mfma_f32_32x32x16_bf16 v[80:95], v[180:183], v[100:103], 0
	v_add_f32_e32 v251, v32, v33
	v_cvt_pk_bf16_f32 v48, v48, v49
	v_exp_f32_e32 v35, v35
	v_add_f32_e32 v251, v34, v251
	v_mfma_f32_32x32x16_bf16 v[64:79], v[152:155], v[104:107], v[64:79]
	v_exp_f32_e32 v36, v36
	v_add_f32_e32 v251, v35, v251
	v_cvt_pk_bf16_f32 v49, v50, v51
	v_exp_f32_e32 v37, v37
	s_waitcnt lgkmcnt(8)
	v_mfma_f32_32x32x16_bf16 v[80:95], v[164:167], v[104:107], v[80:95]
	v_add_f32_e32 v251, v36, v251
	v_exp_f32_e32 v38, v38
	v_add_f32_e32 v251, v37, v251
	v_cvt_pk_bf16_f32 v50, v52, v53
	s_waitcnt lgkmcnt(7)
	v_mfma_f32_32x32x16_bf16 v[64:79], v[156:159], v[108:111], v[64:79]
	v_exp_f32_e32 v39, v39
	v_add_f32_e32 v251, v38, v251
	v_exp_f32_e32 v40, v40
	s_waitcnt lgkmcnt(5)
	v_mfma_f32_32x32x16_bf16 v[80:95], v[176:179], v[108:111], v[80:95]
	v_add_f32_e32 v251, v39, v251
	v_cvt_pk_bf16_f32 v51, v54, v55
	v_exp_f32_e32 v41, v41
	v_add_f32_e32 v251, v40, v251
	v_mfma_f32_32x32x16_bf16 v[64:79], v[140:143], v[112:115], v[64:79]
	v_exp_f32_e32 v42, v42
	v_add_f32_e32 v251, v41, v251
	v_cvt_pk_bf16_f32 v52, v56, v57
	v_exp_f32_e32 v43, v43
	s_mul_i32 s6, s90, 0x3400
	s_add_i32 s7, s6, 0

	v_add_u32_e32 v253, s7, v96
	s_waitcnt vmcnt(1)
	ds_write_b128 v253, v[128:131]
	s_and_saveexec_b64 s[4:5], s[2:3]
	v_add_u32_e32 v253, s7, v185
	ds_write_b128 v253, v[124:127]
	s_or_b64 exec, exec, s[4:5]
	v_lshl_add_u64 v[200:201], s[100:101], 0, v[204:205]

	v_add_u32_e32 v254, 0xc000, v210
	v_lshl_add_u64 v[128:129], s[98:99], 0, v[98:99]
	s_nop 0
	global_load_dwordx4 v[128:131], v[128:129], off
	s_waitcnt vmcnt(1)
	ds_write2_b64 v254, v[132:133], v[134:135] offset1:2

	s_and_saveexec_b64 s[4:5], s[2:3]
	s_cbranch_execz .LatB_h0
	v_lshl_add_u64 v[124:125], s[98:99], 0, v[202:203]
	s_nop 0
	global_load_dwordx4 v[124:127], v[124:125], off
.LatB_h0:
	s_or_b64 exec, exec, s[4:5]
	global_load_dwordx4 v[132:135], v[200:201], off offset:256

	s_waitcnt lgkmcnt(6)
	v_mfma_f32_32x32x16_bf16 v[80:95], v[160:163], v[112:115], v[80:95]
	v_add_f32_e32 v251, v42, v251
	v_exp_f32_e32 v44, v44
	v_add_f32_e32 v251, v43, v251
	v_cvt_pk_bf16_f32 v53, v58, v59
	s_waitcnt lgkmcnt(5)
	v_mfma_f32_32x32x16_bf16 v[64:79], v[148:151], v[116:119], v[64:79]
	v_exp_f32_e32 v45, v45
	v_add_f32_e32 v251, v44, v251
	v_exp_f32_e32 v46, v46
	v_add_f32_e32 v251, v45, v251
	s_waitcnt lgkmcnt(3)
	v_mfma_f32_32x32x16_bf16 v[80:95], v[168:171], v[116:119], v[80:95]
	v_cvt_pk_bf16_f32 v54, v60, v61
	v_exp_f32_e32 v47, v47
	v_add_f32_e32 v251, v46, v251
	v_add_f32_e32 v251, v47, v251
	v_add_u32_e32 v196, v208, v184
	ds_read_b128 v[212:215], v196 offset:44544
	ds_read_b128 v[216:219], v196 offset:39936
	ds_read_b128 v[220:223], v196 offset:39968
	ds_read_b128 v[224:227], v196 offset:44576
	ds_read_b128 v[228:231], v196 offset:40000
	ds_read_b128 v[232:235], v196 offset:44608
	ds_read_b128 v[236:239], v196 offset:40032
	ds_read_b128 v[240:243], v196 offset:44640
	v_mfma_f32_32x32x16_bf16 v[64:79], v[136:139], v[120:123], v[64:79]
	v_cvt_pk_bf16_f32 v55, v62, v63
	v_cvt_pk_bf16_f32 v32, v32, v33
	v_cvt_pk_bf16_f32 v33, v34, v35
	v_cvt_pk_bf16_f32 v34, v36, v37
	v_cvt_pk_bf16_f32 v35, v38, v39
	v_cvt_pk_bf16_f32 v36, v40, v41
	s_waitcnt lgkmcnt(10)
	v_mfma_f32_32x32x16_bf16 v[80:95], v[144:147], v[120:123], v[80:95]
	v_cvt_pk_bf16_f32 v37, v42, v43
	v_cvt_pk_bf16_f32 v38, v44, v45
	v_cvt_pk_bf16_f32 v39, v46, v47
	v_add_f32_e32 v195, v195, v251
	v_add_f32_e32 v198, v198, v195
	s_waitcnt lgkmcnt(0)
	s_barrier

	v_add_u32_e32 v197, s6, v209
	s_setprio 1
	v_mfma_f32_32x32x16_bf16 v[0:15], v[48:51], v[212:215], v[0:15]
	ds_read_b128 v[172:175], v197
	ds_read_b128 v[152:155], v197 offset:32
	v_mfma_f32_32x32x16_bf16 v[0:15], v[52:55], v[224:227], v[0:15]
	ds_read_b128 v[180:183], v197 offset:6656
	ds_read_b128 v[164:167], v197 offset:6688
	v_mfma_f32_32x32x16_bf16 v[0:15], v[32:35], v[232:235], v[0:15]
	ds_read_b128 v[156:159], v197 offset:64
	ds_read_b128 v[140:143], v197 offset:96
	v_exp_f32_e32 v64, v64
	v_exp_f32_e32 v65, v65
	v_exp_f32_e32 v66, v66
	v_add_f32_e32 v195, v64, v65
	v_mfma_f32_32x32x16_bf16 v[0:15], v[36:39], v[240:243], v[0:15]
	s_setprio 0
	ds_read_b128 v[176:179], v197 offset:6720
	ds_read_b128 v[160:163], v197 offset:6752
	v_exp_f32_e32 v67, v67
	v_add_f32_e32 v195, v66, v195
	v_exp_f32_e32 v68, v68
	v_add_f32_e32 v195, v67, v195
	v_exp_f32_e32 v69, v69
	v_add_f32_e32 v195, v68, v195
	v_mfma_f32_32x32x16_bf16 v[16:31], v[48:51], v[216:219], v[16:31]
	ds_read_b128 v[148:151], v197 offset:128
	ds_read_b128 v[136:139], v197 offset:160
	v_exp_f32_e32 v70, v70
	v_add_f32_e32 v195, v69, v195
	v_exp_f32_e32 v71, v71
	v_add_f32_e32 v195, v70, v195
	v_exp_f32_e32 v72, v72
	v_mfma_f32_32x32x16_bf16 v[16:31], v[52:55], v[220:223], v[16:31]
	ds_read_b128 v[168:171], v197 offset:6784
	ds_read_b128 v[144:147], v197 offset:6816
	v_add_f32_e32 v195, v71, v195
	v_exp_f32_e32 v73, v73
	v_add_f32_e32 v195, v72, v195
	v_exp_f32_e32 v74, v74
	v_add_f32_e32 v195, v73, v195
	v_mfma_f32_32x32x16_bf16 v[16:31], v[32:35], v[228:231], v[16:31]
	v_exp_f32_e32 v75, v75
	v_add_f32_e32 v195, v74, v195
	v_exp_f32_e32 v76, v76
	v_add_f32_e32 v195, v75, v195
	v_exp_f32_e32 v77, v77
	v_mfma_f32_32x32x16_bf16 v[16:31], v[36:39], v[236:239], v[16:31]
	v_add_f32_e32 v195, v76, v195
	v_exp_f32_e32 v78, v78
	v_add_f32_e32 v195, v77, v195
	v_exp_f32_e32 v79, v79
	v_add_f32_e32 v195, v78, v195
	v_add_f32_e32 v195, v79, v195
	s_waitcnt lgkmcnt(11)
	v_mfma_f32_32x32x16_bf16 v[48:63], v[172:175], v[100:103], 0
	v_exp_f32_e32 v80, v80
	v_exp_f32_e32 v81, v81
	v_exp_f32_e32 v82, v82
	s_waitcnt lgkmcnt(9)
	v_mfma_f32_32x32x16_bf16 v[32:47], v[180:183], v[100:103], 0
	v_add_f32_e32 v251, v80, v81
	v_cvt_pk_bf16_f32 v64, v64, v65
	v_exp_f32_e32 v83, v83
	v_add_f32_e32 v251, v82, v251
	v_mfma_f32_32x32x16_bf16 v[48:63], v[152:155], v[104:107], v[48:63]
	v_exp_f32_e32 v84, v84
	v_add_f32_e32 v251, v83, v251
	v_cvt_pk_bf16_f32 v65, v66, v67
	v_exp_f32_e32 v85, v85
	s_waitcnt lgkmcnt(8)
	v_mfma_f32_32x32x16_bf16 v[32:47], v[164:167], v[104:107], v[32:47]
	v_add_f32_e32 v251, v84, v251
	v_exp_f32_e32 v86, v86
	v_add_f32_e32 v251, v85, v251
	v_cvt_pk_bf16_f32 v66, v68, v69
	s_waitcnt lgkmcnt(7)
	v_mfma_f32_32x32x16_bf16 v[48:63], v[156:159], v[108:111], v[48:63]
	v_exp_f32_e32 v87, v87
	v_add_f32_e32 v251, v86, v251
	v_exp_f32_e32 v88, v88
	s_waitcnt lgkmcnt(5)
	v_mfma_f32_32x32x16_bf16 v[32:47], v[176:179], v[108:111], v[32:47]
	v_add_f32_e32 v251, v87, v251
	v_cvt_pk_bf16_f32 v67, v70, v71
	v_exp_f32_e32 v89, v89
	v_add_f32_e32 v251, v88, v251
	v_mfma_f32_32x32x16_bf16 v[48:63], v[140:143], v[112:115], v[48:63]
	v_exp_f32_e32 v90, v90
	v_add_f32_e32 v251, v89, v251
	v_cvt_pk_bf16_f32 v68, v72, v73
	v_exp_f32_e32 v91, v91
	s_add_i32 s4, s90, 1
	s_cmp_lg_u32 s90, 2
	s_cselect_b32 s68, s4, 0
	s_mul_i32 s6, s68, 0x3400
	s_add_i32 s7, s6, 0
	s_add_u32 s98, s98, 0x3000
	s_addc_u32 s99, s99, 0

	v_add_u32_e32 v253, s7, v96
	s_waitcnt vmcnt(1)
	ds_write_b128 v253, v[128:131]
	s_and_saveexec_b64 s[4:5], s[2:3]
	v_add_u32_e32 v253, s7, v185
	ds_write_b128 v253, v[124:127]
	s_or_b64 exec, exec, s[4:5]
	v_lshl_add_u64 v[200:201], s[100:101], 0, v[204:205]

	s_waitcnt vmcnt(0)
	ds_write2_b64 v211, v[132:133], v[134:135] offset0:128 offset1:130
	v_lshl_add_u64 v[128:129], s[98:99], 0, v[98:99]
	s_nop 0
	global_load_dwordx4 v[128:131], v[128:129], off

	s_and_saveexec_b64 s[4:5], s[2:3]
	s_cbranch_execz .LatB_h1
	v_lshl_add_u64 v[124:125], s[98:99], 0, v[202:203]
	s_nop 0
	global_load_dwordx4 v[124:127], v[124:125], off
.LatB_h1:
	s_or_b64 exec, exec, s[4:5]
	global_load_dwordx4 v[132:135], v[200:201], off offset:384

	s_sub_u32 s98, s98, 0x3000
	s_subb_u32 s99, s99, 0

	s_waitcnt lgkmcnt(6)
	v_mfma_f32_32x32x16_bf16 v[32:47], v[160:163], v[112:115], v[32:47]
	v_add_f32_e32 v251, v90, v251
	v_exp_f32_e32 v92, v92
	v_add_f32_e32 v251, v91, v251
	v_cvt_pk_bf16_f32 v69, v74, v75
	s_waitcnt lgkmcnt(5)
	v_mfma_f32_32x32x16_bf16 v[48:63], v[148:151], v[116:119], v[48:63]
	v_exp_f32_e32 v93, v93
	v_add_f32_e32 v251, v92, v251
	v_exp_f32_e32 v94, v94
	v_add_f32_e32 v251, v93, v251
	s_waitcnt lgkmcnt(3)
	v_mfma_f32_32x32x16_bf16 v[32:47], v[168:171], v[116:119], v[32:47]
	v_cvt_pk_bf16_f32 v70, v76, v77
	v_exp_f32_e32 v95, v95
	v_add_f32_e32 v251, v94, v251
	v_add_f32_e32 v251, v95, v251
	v_add_u32_e32 v196, v208, v184
	ds_read_b128 v[212:215], v196 offset:53760
	ds_read_b128 v[216:219], v196 offset:49152
	ds_read_b128 v[220:223], v196 offset:49184
	ds_read_b128 v[224:227], v196 offset:53792
	ds_read_b128 v[228:231], v196 offset:49216
	ds_read_b128 v[232:235], v196 offset:53824
	ds_read_b128 v[236:239], v196 offset:49248
	ds_read_b128 v[240:243], v196 offset:53856
	v_mfma_f32_32x32x16_bf16 v[48:63], v[136:139], v[120:123], v[48:63]
	v_cvt_pk_bf16_f32 v71, v78, v79
	v_cvt_pk_bf16_f32 v80, v80, v81
	v_cvt_pk_bf16_f32 v81, v82, v83
	v_cvt_pk_bf16_f32 v82, v84, v85
	v_cvt_pk_bf16_f32 v83, v86, v87
	v_cvt_pk_bf16_f32 v84, v88, v89
	s_waitcnt lgkmcnt(10)
	v_mfma_f32_32x32x16_bf16 v[32:47], v[144:147], v[120:123], v[32:47]
	v_cvt_pk_bf16_f32 v85, v90, v91
	v_cvt_pk_bf16_f32 v86, v92, v93
	v_cvt_pk_bf16_f32 v87, v94, v95
	v_add_f32_e32 v195, v195, v251
	v_add_f32_e32 v198, v198, v195
	s_add_i32 s40, s40, 2
	s_waitcnt lgkmcnt(0)
	s_barrier

	s_cmp_ge_u32 s40, s69
	s_cbranch_scc1 .LatB_yplain

	v_add_u32_e32 v197, s6, v209
	s_setprio 1
	v_mfma_f32_32x32x16_bf16 v[0:15], v[64:67], v[212:215], v[0:15]
	ds_read_b128 v[172:175], v197
	ds_read_b128 v[152:155], v197 offset:32
	v_mfma_f32_32x32x16_bf16 v[0:15], v[68:71], v[224:227], v[0:15]
	ds_read_b128 v[180:183], v197 offset:6656
	ds_read_b128 v[164:167], v197 offset:6688
	v_mfma_f32_32x32x16_bf16 v[0:15], v[80:83], v[232:235], v[0:15]
	ds_read_b128 v[156:159], v197 offset:64
	ds_read_b128 v[140:143], v197 offset:96
	v_exp_f32_e32 v48, v48
	v_exp_f32_e32 v49, v49
	v_exp_f32_e32 v50, v50
	v_add_f32_e32 v195, v48, v49
	v_mfma_f32_32x32x16_bf16 v[0:15], v[84:87], v[240:243], v[0:15]
	s_setprio 0
	ds_read_b128 v[176:179], v197 offset:6720
	ds_read_b128 v[160:163], v197 offset:6752
	v_exp_f32_e32 v51, v51
	v_add_f32_e32 v195, v50, v195
	v_exp_f32_e32 v52, v52
	v_add_f32_e32 v195, v51, v195
	v_exp_f32_e32 v53, v53
	v_add_f32_e32 v195, v52, v195
	v_mfma_f32_32x32x16_bf16 v[16:31], v[64:67], v[216:219], v[16:31]
	ds_read_b128 v[148:151], v197 offset:128
	ds_read_b128 v[136:139], v197 offset:160
	v_exp_f32_e32 v54, v54
	v_add_f32_e32 v195, v53, v195
	v_exp_f32_e32 v55, v55
	v_add_f32_e32 v195, v54, v195
	v_exp_f32_e32 v56, v56
	v_mfma_f32_32x32x16_bf16 v[16:31], v[68:71], v[220:223], v[16:31]
	ds_read_b128 v[168:171], v197 offset:6784
	ds_read_b128 v[144:147], v197 offset:6816
	v_add_f32_e32 v195, v55, v195
	v_exp_f32_e32 v57, v57
	v_add_f32_e32 v195, v56, v195
	v_exp_f32_e32 v58, v58
	v_add_f32_e32 v195, v57, v195
	v_mfma_f32_32x32x16_bf16 v[16:31], v[80:83], v[228:231], v[16:31]
	v_exp_f32_e32 v59, v59
	v_add_f32_e32 v195, v58, v195
	v_exp_f32_e32 v60, v60
	v_add_f32_e32 v195, v59, v195
	v_exp_f32_e32 v61, v61
	v_mfma_f32_32x32x16_bf16 v[16:31], v[84:87], v[236:239], v[16:31]
	v_add_f32_e32 v195, v60, v195
	v_exp_f32_e32 v62, v62
	v_add_f32_e32 v195, v61, v195
	v_exp_f32_e32 v63, v63
	v_add_f32_e32 v195, v62, v195
	v_add_f32_e32 v195, v63, v195
	s_branch .LatB_ctl
